# stack: per-row counted waits in residual epilogues + conv-taps LDS-DMA issued after the K-loop segment's counted vmcnt(8) wait
# speedup vs baseline: 1.0051x; 1.0051x over previous
; #define PG8_STAGE(bufoff, gbase, voff) do { _Pragma("unroll") for (int _i = 0; _i < 2; ++_i) { \
;         const unsigned _m0 = ldsu + (unsigned)(bufoff) + ldsw + (unsigned)(_i * 8192); \
;         asm volatile("s_mov_b32 m0, %2\n\ts_nop 0\n\tglobal_load_lds_dwordx4 %0, %1" :: "v"((voff)[_i]), "s"((const char*)(gbase)), "s"(_m0) : "memory"); } } while (0)
; #define PG8_LDA(dst, b, h) do { _Pragma("unroll") for (int m = 0; m < 4; ++m) _Pragma("unroll") for (int k = 0; k < 2; ++k) dst[m][k] = *(const LAS bf16x8*)(lds + PG8_SA(b, h) + aoff + m * 2048 + k * 1024); } while (0)
; #define PG8_LDB(dst, b, h) do { _Pragma("unroll") for (int n = 0; n < 2; ++n) _Pragma("unroll") for (int k = 0; k < 2; ++k) dst[n][k] = *(const LAS bf16x8*)(lds + bbase[b][h] + n * 2048 + k * 1024); } while (0)
; #define PG8_WAIT_V(n) asm volatile("s_waitcnt vmcnt(" #n ")" ::: "memory")
; #define PG8_WAIT_L(n) asm volatile("s_waitcnt lgkmcnt(" #n ")" ::: "memory")
; #define PG8_BAR __builtin_amdgcn_s_barrier()
; #define PG8_SCHED __builtin_amdgcn_sched_barrier(0)
; template <class Epi>
; __device__ __forceinline__ void gemm_phase(LAS unsigned char* lds, const Gemm g, const StaticOrder& S, const Epi& E) {
;     ...
;         for (int t = 0; t < nt; t += 2) {
;             const bool last = (t == nt - 2);
;             const char* a2 = last ? nA : cA + (size_t)(t + 2) * kstep; const char* b2 = last ? nB : cB + (size_t)(t + 2) * kstep;
;             const char* a3 = a2 + kstep; const char* b3 = b2 + kstep;
;             const char* b1 = cB + (size_t)(t + 1) * kstep;
;             PG8_LDB(B0, 0, 0); PG8_SCHED; PG8_LDA(At, 0, 0); PG8_LDA(At2, 0, 1); PG8_STAGE(PG8_SB(1, 1), b1 + hstepB, voffB);
;             PG8_WAIT_V(8); PG8_WAIT_L(0); PG8_BAR; PG8_MMA2B(0, At, At2, B0); PG8_BAR; PG8_SCHED;
;             PG8_LDB(B0, 0, 1); PG8_STAGE(PG8_SB(0, 0), b2, voffB); PG8_STAGE(PG8_SA(0, 0), a2, voffA); PG8_STAGE(PG8_SA(0, 1), a2 + hstepA, voffA);
;             PG8_WAIT_V(8); PG8_WAIT_L(0); PG8_BAR; PG8_MMA2B(1, At, At2, B0); PG8_BAR; PG8_SCHED;
.LBB0_1027:
	ds_read_b128 v[68:71], v220
	ds_read_b128 v[84:87], v220 offset:1024
	ds_read_b128 v[88:91], v220 offset:2048
	ds_read_b128 v[92:95], v220 offset:3072
	s_add_u32 s12, s10, 0x100
	s_addc_u32 s13, s11, 0
	s_cmp_eq_u32 s69, 12
	s_cselect_b32 s14, s97, vcc_hi
	s_cselect_b32 s15, s7, s68
	s_cselect_b32 s84, vcc_lo, s12
	s_cselect_b32 s85, s39, s13
	s_add_u32 s16, s14, 0x80
	s_addc_u32 s17, s15, 0
	ds_read_b128 v[96:99], v221
	ds_read_b128 v[100:103], v221 offset:1024
	ds_read_b128 v[152:155], v221 offset:2048
	ds_read_b128 v[156:159], v221 offset:3072
	ds_read_b128 v[166:169], v221 offset:4096
	ds_read_b128 v[178:181], v221 offset:5120
	ds_read_b128 v[182:185], v221 offset:6144
	ds_read_b128 v[186:189], v221 offset:7168
	ds_read_b128 v[190:193], v221 offset:16384
	ds_read_b128 v[194:197], v221 offset:17408
	ds_read_b128 v[198:201], v221 offset:18432
	ds_read_b128 v[202:205], v221 offset:19456
	ds_read_b128 v[226:229], v221 offset:20480
	ds_read_b128 v[230:233], v221 offset:21504
	ds_read_b128 v[234:237], v221 offset:22528
	ds_read_b128 v[238:241], v221 offset:23552
	s_add_u32 s10, s10, 0x40080
	s_addc_u32 s11, s11, 0
	s_mov_b32 m0, s58
	s_nop 0
	global_load_lds_dwordx4 v217, s[10:11]
	s_mov_b32 m0, s60
	s_nop 0
	global_load_lds_dwordx4 v219, s[10:11]
	s_waitcnt vmcnt(8)
	s_waitcnt lgkmcnt(0)
	s_barrier
	v_mfma_f32_16x16x32_bf16 v[80:83], v[68:71], v[96:99], v[80:83]
	v_mfma_f32_16x16x32_bf16 v[76:79], v[88:91], v[96:99], v[76:79]
	v_mfma_f32_16x16x32_bf16 v[148:151], v[68:71], v[152:155], v[148:151]
	v_mfma_f32_16x16x32_bf16 v[52:55], v[88:91], v[152:155], v[52:55]
	v_mfma_f32_16x16x32_bf16 v[144:147], v[68:71], v[166:169], v[144:147]
	v_mfma_f32_16x16x32_bf16 v[48:51], v[88:91], v[166:169], v[48:51]
	v_mfma_f32_16x16x32_bf16 v[136:139], v[68:71], v[182:185], v[136:139]
	v_mfma_f32_16x16x32_bf16 v[40:43], v[88:91], v[182:185], v[40:43]
	v_mfma_f32_16x16x32_bf16 v[124:127], v[68:71], v[190:193], v[124:127]
	v_mfma_f32_16x16x32_bf16 v[28:31], v[88:91], v[190:193], v[28:31]
	v_mfma_f32_16x16x32_bf16 v[120:123], v[68:71], v[198:201], v[120:123]
	v_mfma_f32_16x16x32_bf16 v[24:27], v[88:91], v[198:201], v[24:27]
	v_mfma_f32_16x16x32_bf16 v[112:115], v[68:71], v[226:229], v[112:115]
	v_mfma_f32_16x16x32_bf16 v[16:19], v[88:91], v[226:229], v[16:19]
	v_mfma_f32_16x16x32_bf16 v[64:67], v[68:71], v[234:237], v[64:67]
	v_mfma_f32_16x16x32_bf16 v[4:7], v[88:91], v[234:237], v[4:7]
	v_mfma_f32_16x16x32_bf16 v[80:83], v[84:87], v[100:103], v[80:83]
	v_mfma_f32_16x16x32_bf16 v[76:79], v[92:95], v[100:103], v[76:79]
	v_mfma_f32_16x16x32_bf16 v[148:151], v[84:87], v[156:159], v[148:151]
	v_mfma_f32_16x16x32_bf16 v[52:55], v[92:95], v[156:159], v[52:55]
	v_mfma_f32_16x16x32_bf16 v[144:147], v[84:87], v[178:181], v[144:147]
	v_mfma_f32_16x16x32_bf16 v[48:51], v[92:95], v[178:181], v[48:51]
	v_mfma_f32_16x16x32_bf16 v[136:139], v[84:87], v[186:189], v[136:139]
	v_mfma_f32_16x16x32_bf16 v[40:43], v[92:95], v[186:189], v[40:43]
	v_mfma_f32_16x16x32_bf16 v[124:127], v[84:87], v[194:197], v[124:127]
	v_mfma_f32_16x16x32_bf16 v[28:31], v[92:95], v[194:197], v[28:31]
	v_mfma_f32_16x16x32_bf16 v[120:123], v[84:87], v[202:205], v[120:123]
	v_mfma_f32_16x16x32_bf16 v[24:27], v[92:95], v[202:205], v[24:27]
	v_mfma_f32_16x16x32_bf16 v[112:115], v[84:87], v[230:233], v[112:115]
	v_mfma_f32_16x16x32_bf16 v[16:19], v[92:95], v[230:233], v[16:19]
	v_mfma_f32_16x16x32_bf16 v[64:67], v[84:87], v[238:241], v[64:67]
	v_mfma_f32_16x16x32_bf16 v[4:7], v[92:95], v[238:241], v[4:7]
	s_barrier
	ds_read_b128 v[68:71], v222
	ds_read_b128 v[84:87], v222 offset:1024
	ds_read_b128 v[88:91], v222 offset:2048
	ds_read_b128 v[92:95], v222 offset:3072
	s_mov_b32 m0, s48
	s_nop 0
	global_load_lds_dwordx4 v217, s[84:85]
	s_mov_b32 m0, s49
	s_nop 0
	global_load_lds_dwordx4 v219, s[84:85]
	s_mov_b32 m0, s47
	s_nop 0
	global_load_lds_dwordx4 v216, s[14:15]
	s_mov_b32 m0, s50
	s_nop 0
	global_load_lds_dwordx4 v218, s[14:15]
	s_add_u32 s10, s14, 0x40000
	s_addc_u32 s11, s15, 0
	s_mov_b32 m0, s51
	s_nop 0
	global_load_lds_dwordx4 v216, s[10:11]
	s_mov_b32 m0, s52
	s_nop 0
	global_load_lds_dwordx4 v218, s[10:11]
	s_waitcnt vmcnt(8)
	s_waitcnt lgkmcnt(0)
	s_barrier
	v_mfma_f32_16x16x32_bf16 v[72:75], v[68:71], v[96:99], v[72:75]
	v_mfma_f32_16x16x32_bf16 v[56:59], v[88:91], v[96:99], v[56:59]
	v_mfma_f32_16x16x32_bf16 v[44:47], v[88:91], v[152:155], v[44:47]
	v_mfma_f32_16x16x32_bf16 v[36:39], v[88:91], v[166:169], v[36:39]
	v_mfma_f32_16x16x32_bf16 v[128:131], v[68:71], v[182:185], v[128:131]
	v_mfma_f32_16x16x32_bf16 v[32:35], v[88:91], v[182:185], v[32:35]
	v_mfma_f32_16x16x32_bf16 v[116:119], v[68:71], v[190:193], v[116:119]
	v_mfma_f32_16x16x32_bf16 v[20:23], v[88:91], v[190:193], v[20:23]
	v_mfma_f32_16x16x32_bf16 v[108:111], v[68:71], v[198:201], v[108:111]
	v_mfma_f32_16x16x32_bf16 v[12:15], v[88:91], v[198:201], v[12:15]
	v_mfma_f32_16x16x32_bf16 v[104:107], v[68:71], v[226:229], v[104:107]
	v_mfma_f32_16x16x32_bf16 v[8:11], v[88:91], v[226:229], v[8:11]
	v_mfma_f32_16x16x32_bf16 v[60:63], v[68:71], v[234:237], v[60:63]
	v_mfma_f32_16x16x32_bf16 v[0:3], v[88:91], v[234:237], v[0:3]
	v_mfma_f32_16x16x32_bf16 v[72:75], v[84:87], v[100:103], v[72:75]
	v_mfma_f32_16x16x32_bf16 v[56:59], v[92:95], v[100:103], v[56:59]
	v_mfma_f32_16x16x32_bf16 v[96:99], v[68:71], v[152:155], v[140:143]
	v_mfma_f32_16x16x32_bf16 v[44:47], v[92:95], v[156:159], v[44:47]
	v_mfma_f32_16x16x32_bf16 v[100:103], v[68:71], v[166:169], v[132:135]
	v_mfma_f32_16x16x32_bf16 v[36:39], v[92:95], v[178:181], v[36:39]
	v_mfma_f32_16x16x32_bf16 v[128:131], v[84:87], v[186:189], v[128:131]
	v_mfma_f32_16x16x32_bf16 v[32:35], v[92:95], v[186:189], v[32:35]
	v_mfma_f32_16x16x32_bf16 v[116:119], v[84:87], v[194:197], v[116:119]
	v_mfma_f32_16x16x32_bf16 v[20:23], v[92:95], v[194:197], v[20:23]
	v_mfma_f32_16x16x32_bf16 v[108:111], v[84:87], v[202:205], v[108:111]
	v_mfma_f32_16x16x32_bf16 v[12:15], v[92:95], v[202:205], v[12:15]
	v_mfma_f32_16x16x32_bf16 v[104:107], v[84:87], v[230:233], v[104:107]
	v_mfma_f32_16x16x32_bf16 v[8:11], v[92:95], v[230:233], v[8:11]
	v_mfma_f32_16x16x32_bf16 v[60:63], v[84:87], v[238:241], v[60:63]
	v_mfma_f32_16x16x32_bf16 v[0:3], v[92:95], v[238:241], v[0:3]
	v_mfma_f32_16x16x32_bf16 v[96:99], v[84:87], v[156:159], v[96:99]
	v_mfma_f32_16x16x32_bf16 v[100:103], v[84:87], v[178:181], v[100:103]
	s_barrier
; #define LAS __attribute__((address_space(3)))
; #define PG8_STAGE(bufoff, gbase, voff) do { _Pragma("unroll") for (int _i = 0; _i < 2; ++_i) { \
;         const unsigned _m0 = ldsu + (unsigned)(bufoff) + ldsw + (unsigned)(_i * 8192); \
;         asm volatile("s_mov_b32 m0, %2\n\ts_nop 0\n\tglobal_load_lds_dwordx4 %0, %1" :: "v"((voff)[_i]), "s"((const char*)(gbase)), "s"(_m0) : "memory"); } } while (0)
; #define PG8_LDA(dst, b, h) do { _Pragma("unroll") for (int m = 0; m < 4; ++m) _Pragma("unroll") for (int k = 0; k < 2; ++k) dst[m][k] = *(const LAS bf16x8*)(lds + PG8_SA(b, h) + aoff + m * 2048 + k * 1024); } while (0)
; #define PG8_LDB(dst, b, h) do { _Pragma("unroll") for (int n = 0; n < 2; ++n) _Pragma("unroll") for (int k = 0; k < 2; ++k) dst[n][k] = *(const LAS bf16x8*)(lds + bbase[b][h] + n * 2048 + k * 1024); } while (0)
; #define PG8_WAIT_V(n) asm volatile("s_waitcnt vmcnt(" #n ")" ::: "memory")
; #define PG8_WAIT_L(n) asm volatile("s_waitcnt lgkmcnt(" #n ")" ::: "memory")
; #define PG8_BAR __builtin_amdgcn_s_barrier()
; #define PG8_SCHED __builtin_amdgcn_sched_barrier(0)
; template <class Epi>
; __device__ __forceinline__ void gemm_phase(LAS unsigned char* lds, const Gemm g, const StaticOrder& S, const Epi& E) {
;     ...
;             PG8_LDB(B0, 1, 0); PG8_SCHED; PG8_LDA(At, 1, 0); PG8_LDA(At2, 1, 1); PG8_STAGE(PG8_SB(0, 1), b2 + hstepB, voffB);
;             PG8_WAIT_V(8); PG8_WAIT_L(0); PG8_BAR; PG8_MMA2B(0, At, At2, B0); PG8_BAR; PG8_SCHED;
;             PG8_LDB(B0, 1, 1); PG8_STAGE(PG8_SB(1, 0), b3, voffB); PG8_STAGE(PG8_SA(1, 0), a3, voffA); PG8_STAGE(PG8_SA(1, 1), a3 + hstepA, voffA);
;             PG8_WAIT_V(8); PG8_WAIT_L(0); PG8_BAR; PG8_MMA2B(1, At, At2, B0); PG8_BAR; PG8_SCHED;
;     __device__ __forceinline__ void operator()(f32x4 (&acc)[2][2][4][2], const Unit& u, int wr, int wc, int fr, int fq) const {
;     ...
;           else { const int which = t >> 6, j = (t & 63) * 4, bj = j >> 7, c = j & 127; const float* src = (which < 3 ? cw + (size_t)which * NUP : cb) + bj * DFF + u.pn * 128 + c;
;               *(LAS f32x4*)(cwL + which * 256 + j) = *(const f32x4*)src; } }
	ds_read_b128 v[68:71], v223
	ds_read_b128 v[84:87], v223 offset:1024
	ds_read_b128 v[88:91], v223 offset:2048
	ds_read_b128 v[92:95], v223 offset:3072
	ds_read_b128 v[132:135], v221 offset:32768
	ds_read_b128 v[140:143], v221 offset:33792
	ds_read_b128 v[152:155], v221 offset:34816
	ds_read_b128 v[156:159], v221 offset:35840
	ds_read_b128 v[166:169], v221 offset:36864
	ds_read_b128 v[178:181], v221 offset:37888
	ds_read_b128 v[182:185], v221 offset:38912
	ds_read_b128 v[186:189], v221 offset:39936
	ds_read_b128 v[190:193], v221 offset:49152
	ds_read_b128 v[194:197], v221 offset:50176
	ds_read_b128 v[198:201], v221 offset:51200
	ds_read_b128 v[202:205], v221 offset:52224
	ds_read_b128 v[226:229], v221 offset:53248
	ds_read_b128 v[230:233], v221 offset:54272
	ds_read_b128 v[234:237], v221 offset:55296
	ds_read_b128 v[238:241], v221 offset:56320
	s_add_u32 s10, s84, 0x40000
	s_addc_u32 s11, s85, 0
	s_mov_b32 m0, s53
	s_nop 0
	global_load_lds_dwordx4 v217, s[10:11]
	s_mov_b32 m0, s54
	s_nop 0
	global_load_lds_dwordx4 v219, s[10:11]
	s_waitcnt vmcnt(8)
	s_waitcnt lgkmcnt(0)
	s_barrier
	v_mfma_f32_16x16x32_bf16 v[80:83], v[68:71], v[132:135], v[80:83]
	v_mfma_f32_16x16x32_bf16 v[76:79], v[88:91], v[132:135], v[76:79]
	v_mfma_f32_16x16x32_bf16 v[148:151], v[68:71], v[152:155], v[148:151]
	v_mfma_f32_16x16x32_bf16 v[52:55], v[88:91], v[152:155], v[52:55]
	v_mfma_f32_16x16x32_bf16 v[144:147], v[68:71], v[166:169], v[144:147]
	v_mfma_f32_16x16x32_bf16 v[48:51], v[88:91], v[166:169], v[48:51]
	v_mfma_f32_16x16x32_bf16 v[136:139], v[68:71], v[182:185], v[136:139]
	v_mfma_f32_16x16x32_bf16 v[40:43], v[88:91], v[182:185], v[40:43]
	v_mfma_f32_16x16x32_bf16 v[124:127], v[68:71], v[190:193], v[124:127]
	v_mfma_f32_16x16x32_bf16 v[28:31], v[88:91], v[190:193], v[28:31]
	v_mfma_f32_16x16x32_bf16 v[120:123], v[68:71], v[198:201], v[120:123]
	v_mfma_f32_16x16x32_bf16 v[24:27], v[88:91], v[198:201], v[24:27]
	v_mfma_f32_16x16x32_bf16 v[112:115], v[68:71], v[226:229], v[112:115]
	v_mfma_f32_16x16x32_bf16 v[16:19], v[88:91], v[226:229], v[16:19]
	v_mfma_f32_16x16x32_bf16 v[64:67], v[68:71], v[234:237], v[64:67]
	v_mfma_f32_16x16x32_bf16 v[4:7], v[88:91], v[234:237], v[4:7]
	v_mfma_f32_16x16x32_bf16 v[80:83], v[84:87], v[140:143], v[80:83]
	v_mfma_f32_16x16x32_bf16 v[76:79], v[92:95], v[140:143], v[76:79]
	v_mfma_f32_16x16x32_bf16 v[148:151], v[84:87], v[156:159], v[148:151]
	v_mfma_f32_16x16x32_bf16 v[52:55], v[92:95], v[156:159], v[52:55]
	v_mfma_f32_16x16x32_bf16 v[144:147], v[84:87], v[178:181], v[144:147]
	v_mfma_f32_16x16x32_bf16 v[48:51], v[92:95], v[178:181], v[48:51]
	v_mfma_f32_16x16x32_bf16 v[136:139], v[84:87], v[186:189], v[136:139]
	v_mfma_f32_16x16x32_bf16 v[40:43], v[92:95], v[186:189], v[40:43]
	v_mfma_f32_16x16x32_bf16 v[124:127], v[84:87], v[194:197], v[124:127]
	v_mfma_f32_16x16x32_bf16 v[28:31], v[92:95], v[194:197], v[28:31]
	v_mfma_f32_16x16x32_bf16 v[120:123], v[84:87], v[202:205], v[120:123]
	v_mfma_f32_16x16x32_bf16 v[24:27], v[92:95], v[202:205], v[24:27]
	v_mfma_f32_16x16x32_bf16 v[112:115], v[84:87], v[230:233], v[112:115]
	v_mfma_f32_16x16x32_bf16 v[16:19], v[92:95], v[230:233], v[16:19]
	v_mfma_f32_16x16x32_bf16 v[64:67], v[84:87], v[238:241], v[64:67]
	v_mfma_f32_16x16x32_bf16 v[4:7], v[92:95], v[238:241], v[4:7]
	s_barrier
	s_add_u32 s10, s84, 0x80
	ds_read_b128 v[68:71], v224
	ds_read_b128 v[84:87], v224 offset:1024
	ds_read_b128 v[88:91], v224 offset:2048
	ds_read_b128 v[92:95], v224 offset:3072
	s_addc_u32 s11, s85, 0
	s_mov_b32 m0, s88
	s_nop 0
	global_load_lds_dwordx4 v217, s[10:11]
	s_mov_b32 m0, s89
	s_nop 0
	global_load_lds_dwordx4 v219, s[10:11]
	s_mov_b32 m0, s95
	s_nop 0
	global_load_lds_dwordx4 v216, s[16:17]
	s_mov_b32 m0, s37
	s_nop 0
	global_load_lds_dwordx4 v218, s[16:17]
	s_add_u32 s10, s14, 0x40080
	s_addc_u32 s11, s15, 0
	s_mov_b32 m0, s56
	s_nop 0
	global_load_lds_dwordx4 v216, s[10:11]
	s_mov_b32 m0, s57
	s_nop 0
	global_load_lds_dwordx4 v218, s[10:11]
	s_waitcnt vmcnt(8)
	s_waitcnt lgkmcnt(0)
	s_cmp_eq_u32 s69, 12
	s_cbranch_scc0 .Lcw_skip
	s_cmp_eq_u64 s[4:5], 0
	s_cbranch_scc1 .Lcw_skip
	v_lshlrev_b32_e32 v242, 4, v215
	v_add3_u32 v242, v214, s59, v242
	s_lshr_b32 s32, s59, 6
	s_mul_i32 s98, s32, 0x5800
	s_add_u32 s98, s0, s98
	s_addc_u32 s99, s1, 0
	s_cmp_lt_u32 s32, 3
	s_cselect_b32 s98, s98, s2
	s_cselect_b32 s99, s99, s3
	s_lshl_b32 s32, s67, 9
	s_add_u32 s98, s98, s32
	s_addc_u32 s99, s99, 0
	v_bfe_u32 v243, v242, 5, 1
	v_mul_u32_u24_e32 v243, 0x2c00, v243
	v_and_b32_e32 v244, 31, v242
	v_lshl_add_u32 v243, v244, 4, v243
	v_readlane_b32 s32, v252, 44
	s_nop 3
	s_lshl_b32 m0, s59, 4
	s_add_u32 m0, m0, s32
	s_nop 0
	global_load_lds_dwordx4 v243, s[98:99]
; #define PG8_WAIT_V(n) asm volatile("s_waitcnt vmcnt(" #n ")" ::: "memory")
; #define PG8_WAIT_L(n) asm volatile("s_waitcnt lgkmcnt(" #n ")" ::: "memory")
; #define PG8_BAR __builtin_amdgcn_s_barrier()
; #define PG8_SCHED __builtin_amdgcn_sched_barrier(0)
; template <class Epi>
; __device__ __forceinline__ void gemm_phase(LAS unsigned char* lds, const Gemm g, const StaticOrder& S, const Epi& E) {
;     ...
;             PG8_WAIT_V(8); PG8_WAIT_L(0); PG8_BAR; PG8_MMA2B(1, At, At2, B0); PG8_BAR; PG8_SCHED;
;         }
;         if (wr == 0) PG8_BAR;
;     __device__ __forceinline__ void operator()(f32x4 (&acc)[2][2][4][2], const Unit& u, int wr, int wc, int fr, int fq) const {
;     ...
;           if (wr == 0) { const float* sp = ssq + ((size_t)u.pm * 256 + t) * 16; const f32x4 a = *(const f32x4*)sp, b = *(const f32x4*)(sp + 4), c = *(const f32x4*)(sp + 8), d = *(const f32x4*)(sp + 12);
;               const f32x4 q = (a + b) + (c + d); rsL[t] = rsqrtf(((q[0] + q[1]) + (q[2] + q[3])) * (1.0f / 1024.0f) + EPS); }
.Lcw_skip:
	s_barrier
	v_mfma_f32_16x16x32_bf16 v[72:75], v[68:71], v[132:135], v[72:75]
	v_mfma_f32_16x16x32_bf16 v[56:59], v[88:91], v[132:135], v[56:59]
	v_mfma_f32_16x16x32_bf16 v[96:99], v[68:71], v[152:155], v[96:99]
	v_mfma_f32_16x16x32_bf16 v[72:75], v[84:87], v[140:143], v[72:75]
	v_mfma_f32_16x16x32_bf16 v[56:59], v[92:95], v[140:143], v[56:59]
	v_mfma_f32_16x16x32_bf16 v[140:143], v[84:87], v[156:159], v[96:99]
	v_mfma_f32_16x16x32_bf16 v[96:99], v[68:71], v[166:169], v[100:103]
	v_mfma_f32_16x16x32_bf16 v[132:135], v[84:87], v[178:181], v[96:99]
	v_mfma_f32_16x16x32_bf16 v[96:99], v[68:71], v[182:185], v[128:131]
	v_mfma_f32_16x16x32_bf16 v[128:131], v[84:87], v[186:189], v[96:99]
	v_mfma_f32_16x16x32_bf16 v[96:99], v[68:71], v[190:193], v[116:119]
	v_mfma_f32_16x16x32_bf16 v[116:119], v[84:87], v[194:197], v[96:99]
	v_mfma_f32_16x16x32_bf16 v[96:99], v[68:71], v[198:201], v[108:111]
	v_mfma_f32_16x16x32_bf16 v[44:47], v[88:91], v[152:155], v[44:47]
	v_mfma_f32_16x16x32_bf16 v[36:39], v[88:91], v[166:169], v[36:39]
	v_mfma_f32_16x16x32_bf16 v[32:35], v[88:91], v[182:185], v[32:35]
	v_mfma_f32_16x16x32_bf16 v[20:23], v[88:91], v[190:193], v[20:23]
	v_mfma_f32_16x16x32_bf16 v[108:111], v[84:87], v[202:205], v[96:99]
	v_mfma_f32_16x16x32_bf16 v[12:15], v[88:91], v[198:201], v[12:15]
	v_mfma_f32_16x16x32_bf16 v[96:99], v[68:71], v[226:229], v[104:107]
	v_mfma_f32_16x16x32_bf16 v[8:11], v[88:91], v[226:229], v[8:11]
	v_mfma_f32_16x16x32_bf16 v[60:63], v[68:71], v[234:237], v[60:63]
	v_mfma_f32_16x16x32_bf16 v[0:3], v[88:91], v[234:237], v[0:3]
	v_mfma_f32_16x16x32_bf16 v[44:47], v[92:95], v[156:159], v[44:47]
	v_mfma_f32_16x16x32_bf16 v[36:39], v[92:95], v[178:181], v[36:39]
	v_mfma_f32_16x16x32_bf16 v[32:35], v[92:95], v[186:189], v[32:35]
	v_mfma_f32_16x16x32_bf16 v[20:23], v[92:95], v[194:197], v[20:23]
	v_mfma_f32_16x16x32_bf16 v[12:15], v[92:95], v[202:205], v[12:15]
	v_mfma_f32_16x16x32_bf16 v[104:107], v[84:87], v[230:233], v[96:99]
	v_mfma_f32_16x16x32_bf16 v[8:11], v[92:95], v[230:233], v[8:11]
	v_mfma_f32_16x16x32_bf16 v[60:63], v[84:87], v[238:241], v[60:63]
	v_mfma_f32_16x16x32_bf16 v[0:3], v[92:95], v[238:241], v[0:3]
	s_barrier
	s_add_i32 s69, s69, 2
	s_add_u32 vcc_hi, vcc_hi, 0x100
	s_addc_u32 s68, s68, 0
	s_cmp_gt_u32 s69, 13
	s_mov_b64 s[10:11], s[12:13]
	s_cbranch_scc0 .LBB0_1027
	s_and_b64 vcc, exec, s[90:91]
	s_cbranch_vccz .LBB0_1030
	v_lshlrev_b32_e32 v68, 4, v215
	v_add3_u32 v68, v214, s59, v68
	s_ashr_i32 s97, s96, 31
	s_lshl_b64 s[12:13], s[96:97], 14
	v_ashrrev_i32_e32 v69, 31, v68
	s_add_u32 s12, s18, s12
	s_addc_u32 s13, s19, s13
	v_lshlrev_b64 v[70:71], 6, v[68:69]
	v_lshl_add_u64 v[70:71], s[12:13], 0, v[70:71]
	global_load_dwordx4 v[86:89], v[70:71], off
	global_load_dwordx4 v[90:93], v[70:71], off offset:16
	global_load_dwordx4 v[94:97], v[70:71], off offset:32
	global_load_dwordx4 v[98:101], v[70:71], off offset:48
	s_barrier
